# P2: relaxed tile-boundary waits, whole-line q/k/v/z_a stores and permlane norm sums together
# baseline (speedup 1.0000x reference)
; __device__ __forceinline__ float silu(float x) { return x * sigm(x); }
;     __device__ __forceinline__ void operator()(const f32x4 (&acc)[2][2][4][2], const Unit& u, int wr, int wc, int fr, int fq) const {
;     ...
;         } else {
;             size_t doff; int ld, tcol, act;
;             if (pn < 6) { doff = OFF_V; ld = 512; tcol = (pn - 4) * 256; act = 0; }
;             else { doff = OFF_SZA; ld = 512; tcol = (pn - 6) * 256; act = 1; }
;             bf16_t* dst = (bf16_t*)(ws + doff);
;             const int colb = tcol + 64 * wc + 8 * fq;
; #pragma unroll
;             for (int ai = 0; ai < 2; ++ai)
; #pragma unroll
;                 for (int m = 0; m < 4; ++m) { bf16_t* rowp = dst + (row0 + ai * HALF + m * 16) * ld + colb;
; #pragma unroll
;                     for (int bj = 0; bj < 2; ++bj) { f32x4 v0 = acc[ai][bj][m][0], v1 = acc[ai][bj][m][1];
;                         if (act == 1) { v0[0] = silu(v0[0]); v0[1] = silu(v0[1]); v0[2] = silu(v0[2]); v0[3] = silu(v0[3]); v1[0] = silu(v1[0]); v1[1] = silu(v1[1]); v1[2] = silu(v1[2]); v1[3] = silu(v1[3]); }
.LBB0_240:
	s_and_b32 s6, s40, 0x7ffffff8
	s_cmp_lg_u32 s6, 8
	s_mov_b64 s[6:7], -1
	s_cbranch_scc0 .LBB0_278
	s_cmp_lt_u32 s40, 16
	s_cbranch_scc0 .LBB0_275
	v_mbcnt_lo_u32_b32 v236, -1, 0
	v_mbcnt_hi_u32_b32 v236, -1, v236
	v_bfe_u32 v238, v236, 3, 1
	v_mul_i32_i24_e32 v236, 0xffffe040, v238
	v_ashrrev_i32_e32 v237, 31, v236
	v_mul_i32_i24_e32 v238, 0xffffe040, v238
	v_add_u32_e32 v238, 0x2000, v238
	v_mov_b32_e32 v239, 0
	s_mov_b32 s89, 2
	s_cmp_gt_u32 s40, 5
	s_cselect_b64 s[42:43], -1, 0
	s_cmp_lt_u32 s40, 6
	v_mov_b32_e32 v159, v125
	v_mov_b32_e32 v158, v124
	v_mov_b32_e32 v163, v123
	v_mov_b32_e32 v162, v122
	v_mov_b32_e32 v157, v129
	v_mov_b32_e32 v156, v128
	v_mov_b32_e32 v161, v127
	v_mov_b32_e32 v160, v126
	s_cbranch_scc1 .LBB0_244
	v_mul_f32_e32 v138, 0xbfb8aa3b, v126
	v_exp_f32_e32 v138, v138
	v_mul_f32_e32 v154, 0xbfb8aa3b, v127
	v_mul_f32_e32 v155, 0xbfb8aa3b, v128
	v_exp_f32_e32 v156, v154
	v_exp_f32_e32 v157, v155
	v_add_f32_e32 v138, 1.0, v138
	v_rcp_f32_e32 v154, v138
	v_add_f32_e32 v138, 1.0, v156
	v_mul_f32_e32 v156, 0xbfb8aa3b, v129
	v_rcp_f32_e32 v155, v138
	v_add_f32_e32 v138, 1.0, v157
	v_exp_f32_e32 v157, v156
	v_mul_f32_e32 v156, 0xbfb8aa3b, v122
	v_exp_f32_e32 v158, v156
	v_rcp_f32_e32 v156, v138
	v_add_f32_e32 v138, 1.0, v157
	v_rcp_f32_e32 v157, v138
	v_add_f32_e32 v138, 1.0, v158
	v_rcp_f32_e32 v162, v138
	v_mul_f32_e32 v138, 0xbfb8aa3b, v123
	v_mul_f32_e32 v158, 0xbfb8aa3b, v124
	v_mul_f32_e32 v159, 0xbfb8aa3b, v125
	v_exp_f32_e32 v138, v138
	v_exp_f32_e32 v158, v158
	v_exp_f32_e32 v159, v159
	v_pk_mul_f32 v[156:157], v[128:129], v[156:157]
	v_add_f32_e32 v138, 1.0, v138
	v_add_f32_e32 v158, 1.0, v158
	v_add_f32_e32 v159, 1.0, v159
	v_rcp_f32_e32 v158, v158
	v_rcp_f32_e32 v159, v159
	v_rcp_f32_e32 v163, v138
	v_pk_mul_f32 v[160:161], v[126:127], v[154:155]
	v_pk_mul_f32 v[158:159], v[124:125], v[158:159]
	v_pk_mul_f32 v[162:163], v[122:123], v[162:163]

; __device__ __forceinline__ unsigned cvt_pk_bf16(float lo, float hi) { unsigned r; asm volatile("v_cvt_pk_bf16_f32 %0, %1, %2" : "=v"(r) : "v"(lo), "v"(hi)); return r; }
;     __device__ __forceinline__ void operator()(const f32x4 (&acc)[2][2][4][2], const Unit& u, int wr, int wc, int fr, int fq) const {
;     ...
;             const bool isq = pn < 2; const float* g = isq ? qg : kg; bf16_t* dst = (bf16_t*)(ws + (isq ? OFF_Q : OFF_K)); const float sc = isq ? qscale : 1.0f;
;             const int colb = (pn & 1) * 256 + 64 * wc + 8 * fq;
;             f32x4 gv[2][2];
; #pragma unroll
;             for (int bj = 0; bj < 2; ++bj)
; #pragma unroll
;                 for (int n = 0; n < 2; ++n) gv[bj][n] = *(const f32x4*)(g + 32 * bj + 8 * fq + 4 * n) * sc;
; #pragma unroll
;             for (int ai = 0; ai < 2; ++ai)
; #pragma unroll
;                 for (int m = 0; m < 4; ++m) {
;                     float ss = 0.f;
; #pragma unroll
;                     for (int bj = 0; bj < 2; ++bj)
; #pragma unroll
;                         for (int n = 0; n < 2; ++n) { const f32x4 x = acc[ai][bj][m][n]; ss += (x[0] * x[0] + x[1] * x[1]) + (x[2] * x[2] + x[3] * x[3]); }
;                     ss += __shfl_xor(ss, 16); ss += __shfl_xor(ss, 32);
;                     const float rstd = __builtin_amdgcn_rsqf(ss * (1.0f / 64.0f) + eps);
;                     bf16_t* rowp = dst + (row0 + ai * HALF + m * 16) * 512 + colb;
; #pragma unroll
;                     for (int bj = 0; bj < 2; ++bj) { const f32x4 v0 = acc[ai][bj][m][0] * rstd * gv[bj][0], v1 = acc[ai][bj][m][1] * rstd * gv[bj][1];
;                         u32x4 w; w.x = cvt_pk_bf16(v0[0], v0[1]); w.y = cvt_pk_bf16(v0[2], v0[3]); w.z = cvt_pk_bf16(v1[0], v1[1]); w.w = cvt_pk_bf16(v1[2], v1[3]);
;                         *(u32x4*)(rowp + 32 * bj) = w; }
.LBB0_281:
	v_mbcnt_lo_u32_b32 v236, -1, 0
	v_mbcnt_hi_u32_b32 v236, -1, v236
	v_bfe_u32 v238, v236, 3, 1
	v_mul_i32_i24_e32 v236, 0xffffe040, v238
	v_ashrrev_i32_e32 v237, 31, v236
	v_mul_i32_i24_e32 v238, 0xffffe040, v238
	v_add_u32_e32 v238, 0x2000, v238
	v_mov_b32_e32 v239, 0
	s_mov_b32 s89, 2
	s_lshl_b32 s31, s40, 8
	s_cmp_lt_i32 s40, 2
	s_cselect_b64 vcc, -1, 0
	s_and_b64 s[6:7], vcc, exec
	s_cselect_b32 s7, s9, s11
	s_cselect_b32 s6, s8, s10
	global_load_dwordx4 v[156:159], v179, s[6:7]
	global_load_dwordx4 v[160:163], v179, s[6:7] offset:16
	global_load_dwordx4 v[182:185], v179, s[6:7] offset:128
	global_load_dwordx4 v[186:189], v179, s[6:7] offset:144
	v_pk_mul_f32 v[154:155], v[128:129], v[128:129]
	v_pk_mul_f32 v[192:193], v[126:127], v[126:127]
	v_pk_mul_f32 v[194:195], v[124:125], v[124:125]
	v_pk_mul_f32 v[196:197], v[122:123], v[122:123]
	v_pk_mov_b32 v[208:209], v[192:193], v[154:155] op_sel:[1,0]
	v_mov_b32_e32 v193, v155
	v_pk_mov_b32 v[154:155], v[196:197], v[194:195] op_sel:[1,0]
	v_mov_b32_e32 v197, v195
	v_mul_f32_e32 v138, v119, v119
	v_mul_f32_e32 v198, v121, v121
	v_pk_add_f32 v[192:193], v[208:209], v[192:193]
	v_pk_add_f32 v[154:155], v[154:155], v[196:197]
	v_mul_f32_e32 v191, v106, v106
	v_mul_f32_e32 v212, v107, v107
	v_mul_f32_e32 v213, v108, v108
	v_mul_f32_e32 v214, v109, v109
	v_pk_fma_f32 v[194:195], v[118:119], v[118:119], v[138:139] op_sel_hi:[1,1,0]
	v_pk_fma_f32 v[198:199], v[120:121], v[120:121], v[198:199] op_sel_hi:[1,1,0]
	v_pk_add_f32 v[192:193], v[192:193], v[192:193] op_sel:[0,1] op_sel_hi:[1,0]
	v_pk_add_f32 v[154:155], v[154:155], v[154:155] op_sel:[0,1] op_sel_hi:[1,0]
	v_mov_b32_e32 v195, v213
	v_mov_b32_e32 v199, v214
	v_mov_b32_e32 v193, v191
	v_mov_b32_e32 v155, v212
	v_pk_add_f32 v[194:195], v[194:195], v[198:199]
	v_pk_add_f32 v[154:155], v[192:193], v[154:155]
	s_cselect_b32 s6, s76, 0x8000000
	v_pk_add_f32 v[154:155], v[154:155], v[194:195]
	s_add_u32 s6, s12, s6
	v_add_f32_e32 v138, v154, v155
	v_mov_b32_e32 v154, v138
	v_mov_b32_e32 v252, v138
	s_addc_u32 s7, s13, 0
	s_and_b32 s31, s31, 0x100
	v_or_b32_e32 v155, s31, v175
	v_pk_mul_f32 v[200:201], v[116:117], v[116:117]
	s_nop 1
	v_permlane16_swap_b32_e32 v154, v252
	v_add_f32_e32 v138, v252, v154
	v_mov_b32_e32 v154, v138
	v_mov_b32_e32 v252, v138
	v_pk_mul_f32 v[202:203], v[114:115], v[114:115]
	v_pk_mul_f32 v[204:205], v[112:113], v[112:113]
	v_pk_mul_f32 v[206:207], v[110:111], v[110:111]
	v_cndmask_b32_e32 v190, 1.0, v181, vcc
	s_nop 1
	v_permlane32_swap_b32_e32 v154, v252
	v_add_f32_e32 v138, v252, v154
	v_fmamk_f32 v138, v138, 0x3c800000, v180
	v_rsq_f32_e32 v196, v138
	v_lshlrev_b32_e32 v138, 1, v155
	v_lshlrev_b64 v[152:153], 10, v[152:153]
	v_pk_mov_b32 v[210:211], v[202:203], v[200:201] op_sel:[1,0]
	v_mov_b32_e32 v203, v201
	v_pk_mov_b32 v[200:201], v[206:207], v[204:205] op_sel:[1,0]
	v_mov_b32_e32 v207, v205
	v_lshl_add_u64 v[154:155], s[6:7], 0, v[138:139]
	v_pk_add_f32 v[194:195], v[200:201], v[206:207]
	v_lshl_add_u64 v[152:153], v[154:155], 0, v[152:153]
	v_pk_mul_f32 v[198:199], v[126:127], v[196:197] op_sel_hi:[1,0]
	v_pk_mul_f32 v[200:201], v[128:129], v[196:197] op_sel_hi:[1,0]
	v_pk_add_f32 v[192:193], v[210:211], v[202:203]
	v_pk_mul_f32 v[202:203], v[122:123], v[196:197] op_sel_hi:[1,0]
	v_pk_mul_f32 v[204:205], v[124:125], v[196:197] op_sel_hi:[1,0]
	v_mul_f32_e32 v215, v90, v90
	v_mul_f32_e32 v216, v91, v91
	v_mul_f32_e32 v138, v103, v103
	v_pk_mul_f32 v[206:207], v[118:119], v[196:197] op_sel_hi:[1,0]
	v_pk_mul_f32 v[208:209], v[120:121], v[196:197] op_sel_hi:[1,0]
	v_pk_mul_f32 v[106:107], v[106:107], v[196:197] op_sel_hi:[1,0]
	v_pk_mul_f32 v[108:109], v[108:109], v[196:197] op_sel_hi:[1,0]
	s_waitcnt vmcnt(0)
	v_pk_mul_f32 v[154:155], v[190:191], v[158:159] op_sel_hi:[0,1]
	v_pk_mul_f32 v[156:157], v[190:191], v[156:157] op_sel_hi:[0,1]
	v_pk_mul_f32 v[126:127], v[190:191], v[162:163] op_sel_hi:[0,1]
	v_pk_mul_f32 v[128:129], v[190:191], v[160:161] op_sel_hi:[0,1]
	v_pk_mul_f32 v[160:161], v[154:155], v[200:201]
	v_pk_mul_f32 v[158:159], v[156:157], v[198:199]
	v_pk_mul_f32 v[124:125], v[190:191], v[182:183] op_sel_hi:[0,1]
	v_pk_mul_f32 v[162:163], v[126:127], v[204:205]
	v_pk_mul_f32 v[182:183], v[128:129], v[202:203]
	v_cvt_pk_bf16_f32 v158, v158, v159
	v_cvt_pk_bf16_f32 v159, v160, v161
	v_pk_mul_f32 v[118:119], v[190:191], v[188:189] op_sel_hi:[0,1]
	v_cvt_pk_bf16_f32 v160, v182, v183
	v_cvt_pk_bf16_f32 v161, v162, v163
	v_mov_b32_e32 v244, v158
	v_mov_b32_e32 v245, v159
	v_mov_b32_e32 v246, v160
	v_mov_b32_e32 v247, v161
	v_lshl_add_u64 v[240:241], v[152:153], 0, v[236:237]
	v_lshl_add_u64 v[242:243], v[152:153], 0, v[238:239]
	v_mul_f32_e32 v162, v92, v92
	v_mul_f32_e32 v182, v93, v93
	v_pk_add_f32 v[158:159], v[192:193], v[192:193] op_sel:[0,1] op_sel_hi:[1,0]
	v_pk_add_f32 v[160:161], v[194:195], v[194:195] op_sel:[0,1] op_sel_hi:[1,0]
	v_mov_b32_e32 v159, v215
	v_mov_b32_e32 v161, v216
	v_pk_add_f32 v[158:159], v[158:159], v[160:161]
	v_pk_fma_f32 v[160:161], v[102:103], v[102:103], v[138:139] op_sel_hi:[1,1,0]
	v_mul_f32_e32 v138, v105, v105
	v_mov_b32_e32 v161, v162
	v_pk_fma_f32 v[162:163], v[104:105], v[104:105], v[138:139] op_sel_hi:[1,1,0]
	v_pk_mul_f32 v[120:121], v[190:191], v[186:187] op_sel_hi:[0,1]
	v_mov_b32_e32 v163, v182
	v_pk_add_f32 v[160:161], v[160:161], v[162:163]
	v_pk_mul_f32 v[122:123], v[190:191], v[184:185] op_sel_hi:[0,1]
	v_pk_add_f32 v[158:159], v[158:159], v[160:161]
	v_pk_mul_f32 v[160:161], v[124:125], v[206:207]
	v_add_f32_e32 v138, v158, v159
	v_mov_b32_e32 v162, v138
	v_mov_b32_e32 v252, v138
	v_pk_mul_f32 v[158:159], v[122:123], v[208:209]
	s_nop 1
; __device__ __forceinline__ unsigned cvt_pk_bf16(float lo, float hi) { unsigned r; asm volatile("v_cvt_pk_bf16_f32 %0, %1, %2" : "=v"(r) : "v"(lo), "v"(hi)); return r; }
;     __device__ __forceinline__ void operator()(const f32x4 (&acc)[2][2][4][2], const Unit& u, int wr, int wc, int fr, int fq) const {
;     ...
;                 for (int m = 0; m < 4; ++m) {
;                     float ss = 0.f;
; #pragma unroll
;                     for (int bj = 0; bj < 2; ++bj)
; #pragma unroll
;                         for (int n = 0; n < 2; ++n) { const f32x4 x = acc[ai][bj][m][n]; ss += (x[0] * x[0] + x[1] * x[1]) + (x[2] * x[2] + x[3] * x[3]); }
;                     ss += __shfl_xor(ss, 16); ss += __shfl_xor(ss, 32);
;                     const float rstd = __builtin_amdgcn_rsqf(ss * (1.0f / 64.0f) + eps);
;                     bf16_t* rowp = dst + (row0 + ai * HALF + m * 16) * 512 + colb;
; #pragma unroll
;                     for (int bj = 0; bj < 2; ++bj) { const f32x4 v0 = acc[ai][bj][m][0] * rstd * gv[bj][0], v1 = acc[ai][bj][m][1] * rstd * gv[bj][1];
;                         u32x4 w; w.x = cvt_pk_bf16(v0[0], v0[1]); w.y = cvt_pk_bf16(v0[2], v0[3]); w.z = cvt_pk_bf16(v1[0], v1[1]); w.w = cvt_pk_bf16(v1[2], v1[3]);
;                         *(u32x4*)(rowp + 32 * bj) = w; }
	v_permlane16_swap_b32_e32 v162, v252
	v_add_f32_e32 v138, v252, v162
	v_mov_b32_e32 v182, v138
	v_mov_b32_e32 v252, v138
	v_pk_mul_f32 v[162:163], v[118:119], v[108:109]
	v_pk_mul_f32 v[108:109], v[120:121], v[106:107]
	v_cvt_pk_bf16_f32 v106, v160, v161
	v_cvt_pk_bf16_f32 v107, v158, v159
	s_nop 1
	v_permlane32_swap_b32_e32 v182, v252
	v_add_f32_e32 v138, v252, v182
	v_fmamk_f32 v138, v138, 0x3c800000, v180
	v_rsq_f32_e32 v138, v138
	v_cvt_pk_bf16_f32 v108, v108, v109
	v_cvt_pk_bf16_f32 v109, v162, v163
	s_nop 0
	v_mov_b32_e32 v248, v106
	v_mov_b32_e32 v249, v107
	v_mov_b32_e32 v250, v108
	v_mov_b32_e32 v251, v109
	v_mov_b32_dpp v248, v244 row_shl:8 row_mask:0xf bank_mask:0x3
	v_mov_b32_dpp v249, v245 row_shl:8 row_mask:0xf bank_mask:0x3
	v_mov_b32_dpp v250, v246 row_shl:8 row_mask:0xf bank_mask:0x3
	v_mov_b32_dpp v251, v247 row_shl:8 row_mask:0xf bank_mask:0x3
	v_mov_b32_dpp v244, v106 row_shr:8 row_mask:0xf bank_mask:0xc
	v_mov_b32_dpp v245, v107 row_shr:8 row_mask:0xf bank_mask:0xc
	v_mov_b32_dpp v246, v108 row_shr:8 row_mask:0xf bank_mask:0xc
	v_mov_b32_dpp v247, v109 row_shr:8 row_mask:0xf bank_mask:0xc
	global_store_dwordx4 v[240:241], v[244:247], off
	global_store_dwordx4 v[242:243], v[248:251], off
	v_pk_mul_f32 v[110:111], v[110:111], v[138:139] op_sel_hi:[1,0]
	v_pk_mul_f32 v[112:113], v[112:113], v[138:139] op_sel_hi:[1,0]
	v_pk_mul_f32 v[106:107], v[114:115], v[138:139] op_sel_hi:[1,0]
	v_pk_mul_f32 v[108:109], v[116:117], v[138:139] op_sel_hi:[1,0]
	v_pk_mul_f32 v[106:107], v[156:157], v[106:107]
	v_pk_mul_f32 v[108:109], v[154:155], v[108:109]
	v_pk_mul_f32 v[110:111], v[128:129], v[110:111]
	v_cvt_pk_bf16_f32 v106, v106, v107
	v_cvt_pk_bf16_f32 v107, v108, v109
	v_pk_mul_f32 v[112:113], v[126:127], v[112:113]
	v_cvt_pk_bf16_f32 v108, v110, v111
	v_add_co_u32_e32 v110, vcc, s56, v152
	v_cvt_pk_bf16_f32 v109, v112, v113
	v_pk_mul_f32 v[102:103], v[102:103], v[138:139] op_sel_hi:[1,0]
	s_nop 0
	v_addc_co_u32_e32 v111, vcc, 0, v153, vcc
	v_mov_b32_e32 v244, v106
	v_mov_b32_e32 v245, v107
	v_mov_b32_e32 v246, v108
	v_mov_b32_e32 v247, v109
	v_lshl_add_u64 v[240:241], v[110:111], 0, v[236:237]
	v_lshl_add_u64 v[242:243], v[110:111], 0, v[238:239]
	v_pk_mul_f32 v[102:103], v[124:125], v[102:103]
	v_pk_mul_f32 v[90:91], v[90:91], v[138:139] op_sel_hi:[1,0]
	v_pk_mul_f32 v[106:107], v[100:101], v[100:101]
	v_pk_mul_f32 v[108:109], v[98:99], v[98:99]
	v_pk_mul_f32 v[92:93], v[92:93], v[138:139] op_sel_hi:[1,0]
	v_pk_mov_b32 v[112:113], v[108:109], v[106:107] op_sel:[1,0]
	v_mov_b32_e32 v109, v107
	v_pk_add_f32 v[106:107], v[112:113], v[108:109]
	v_pk_mul_f32 v[108:109], v[96:97], v[96:97]
	v_pk_mul_f32 v[112:113], v[94:95], v[94:95]
	v_pk_add_f32 v[106:107], v[106:107], v[106:107] op_sel:[0,1] op_sel_hi:[1,0]
	v_pk_mov_b32 v[114:115], v[112:113], v[108:109] op_sel:[1,0]
	v_mov_b32_e32 v113, v109
	v_pk_add_f32 v[108:109], v[114:115], v[112:113]
	v_mul_f32_e32 v112, v74, v74
	v_mul_f32_e32 v113, v75, v75
	v_pk_add_f32 v[108:109], v[108:109], v[108:109] op_sel:[0,1] op_sel_hi:[1,0]
	v_mov_b32_e32 v107, v112
	v_mov_b32_e32 v109, v113
	v_pk_add_f32 v[106:107], v[106:107], v[108:109]
	v_mul_f32_e32 v108, v87, v87
	v_mul_f32_e32 v112, v89, v89
	v_mul_f32_e32 v114, v76, v76
	v_mul_f32_e32 v115, v77, v77
	v_pk_fma_f32 v[108:109], v[86:87], v[86:87], v[108:109] op_sel_hi:[1,1,0]
	v_pk_fma_f32 v[112:113], v[88:89], v[88:89], v[112:113] op_sel_hi:[1,1,0]
	v_mov_b32_e32 v109, v114
	v_mov_b32_e32 v113, v115
	v_pk_add_f32 v[108:109], v[108:109], v[112:113]
	v_pk_mul_f32 v[104:105], v[104:105], v[138:139] op_sel_hi:[1,0]
	v_pk_add_f32 v[106:107], v[106:107], v[108:109]
	v_pk_mul_f32 v[104:105], v[122:123], v[104:105]
	v_add_f32_e32 v106, v106, v107
	v_mov_b32_e32 v107, v106
	v_mov_b32_e32 v252, v106
	s_nop 1
	v_permlane16_swap_b32_e32 v107, v252
	v_add_f32_e32 v108, v252, v107
	v_mov_b32_e32 v109, v108
	v_mov_b32_e32 v252, v108
	v_pk_mul_f32 v[106:107], v[118:119], v[92:93]
	v_pk_mul_f32 v[92:93], v[120:121], v[90:91]
	v_cvt_pk_bf16_f32 v90, v102, v103
	v_cvt_pk_bf16_f32 v91, v104, v105
	s_nop 1
	v_permlane32_swap_b32_e32 v109, v252
	v_add_f32_e32 v102, v252, v109
	v_fmamk_f32 v102, v102, 0x3c800000, v180
	v_rsq_f32_e32 v102, v102
	v_cvt_pk_bf16_f32 v92, v92, v93
	v_cvt_pk_bf16_f32 v93, v106, v107
	s_nop 0
	v_mov_b32_e32 v248, v90
	v_mov_b32_e32 v249, v91
	v_mov_b32_e32 v250, v92
	v_mov_b32_e32 v251, v93
	v_mov_b32_dpp v248, v244 row_shl:8 row_mask:0xf bank_mask:0x3
	v_mov_b32_dpp v249, v245 row_shl:8 row_mask:0xf bank_mask:0x3
	v_mov_b32_dpp v250, v246 row_shl:8 row_mask:0xf bank_mask:0x3
	v_mov_b32_dpp v251, v247 row_shl:8 row_mask:0xf bank_mask:0x3
	v_mov_b32_dpp v244, v90 row_shr:8 row_mask:0xf bank_mask:0xc
	v_mov_b32_dpp v245, v91 row_shr:8 row_mask:0xf bank_mask:0xc
	v_mov_b32_dpp v246, v92 row_shr:8 row_mask:0xf bank_mask:0xc
	v_mov_b32_dpp v247, v93 row_shr:8 row_mask:0xf bank_mask:0xc
	global_store_dwordx4 v[240:241], v[244:247], off
	global_store_dwordx4 v[242:243], v[248:251], off
	v_pk_mul_f32 v[94:95], v[94:95], v[102:103] op_sel_hi:[1,0]
	v_pk_mul_f32 v[96:97], v[96:97], v[102:103] op_sel_hi:[1,0]
	v_pk_mul_f32 v[90:91], v[98:99], v[102:103] op_sel_hi:[1,0]
	v_pk_mul_f32 v[92:93], v[100:101], v[102:103] op_sel_hi:[1,0]
	v_pk_mul_f32 v[90:91], v[156:157], v[90:91]
	v_pk_mul_f32 v[92:93], v[154:155], v[92:93]
	v_pk_mul_f32 v[94:95], v[128:129], v[94:95]
	v_cvt_pk_bf16_f32 v90, v90, v91
	v_cvt_pk_bf16_f32 v91, v92, v93
	v_pk_mul_f32 v[96:97], v[126:127], v[96:97]
	v_cvt_pk_bf16_f32 v92, v94, v95
	v_add_co_u32_e32 v94, vcc, s60, v152
	v_cvt_pk_bf16_f32 v93, v96, v97
	v_pk_mul_f32 v[86:87], v[86:87], v[102:103] op_sel_hi:[1,0]
	s_nop 0
; __device__ __forceinline__ unsigned cvt_pk_bf16(float lo, float hi) { unsigned r; asm volatile("v_cvt_pk_bf16_f32 %0, %1, %2" : "=v"(r) : "v"(lo), "v"(hi)); return r; }
;     __device__ __forceinline__ void operator()(const f32x4 (&acc)[2][2][4][2], const Unit& u, int wr, int wc, int fr, int fq) const {
;     ...
;                 for (int m = 0; m < 4; ++m) {
;                     float ss = 0.f;
; #pragma unroll
;                     for (int bj = 0; bj < 2; ++bj)
; #pragma unroll
;                         for (int n = 0; n < 2; ++n) { const f32x4 x = acc[ai][bj][m][n]; ss += (x[0] * x[0] + x[1] * x[1]) + (x[2] * x[2] + x[3] * x[3]); }
;                     ss += __shfl_xor(ss, 16); ss += __shfl_xor(ss, 32);
;                     const float rstd = __builtin_amdgcn_rsqf(ss * (1.0f / 64.0f) + eps);
;                     bf16_t* rowp = dst + (row0 + ai * HALF + m * 16) * 512 + colb;
; #pragma unroll
;                     for (int bj = 0; bj < 2; ++bj) { const f32x4 v0 = acc[ai][bj][m][0] * rstd * gv[bj][0], v1 = acc[ai][bj][m][1] * rstd * gv[bj][1];
;                         u32x4 w; w.x = cvt_pk_bf16(v0[0], v0[1]); w.y = cvt_pk_bf16(v0[2], v0[3]); w.z = cvt_pk_bf16(v1[0], v1[1]); w.w = cvt_pk_bf16(v1[2], v1[3]);
;                         *(u32x4*)(rowp + 32 * bj) = w; }
	v_addc_co_u32_e32 v95, vcc, 0, v153, vcc
	v_mov_b32_e32 v244, v90
	v_mov_b32_e32 v245, v91
	v_mov_b32_e32 v246, v92
	v_mov_b32_e32 v247, v93
	v_lshl_add_u64 v[240:241], v[94:95], 0, v[236:237]
	v_lshl_add_u64 v[242:243], v[94:95], 0, v[238:239]
	v_pk_mul_f32 v[86:87], v[124:125], v[86:87]
	v_pk_mul_f32 v[74:75], v[74:75], v[102:103] op_sel_hi:[1,0]
	v_pk_mul_f32 v[90:91], v[84:85], v[84:85]
	v_pk_mul_f32 v[92:93], v[82:83], v[82:83]
	v_pk_mul_f32 v[76:77], v[76:77], v[102:103] op_sel_hi:[1,0]
	v_pk_mov_b32 v[96:97], v[92:93], v[90:91] op_sel:[1,0]
	v_mov_b32_e32 v93, v91
	v_pk_add_f32 v[90:91], v[96:97], v[92:93]
	v_pk_mul_f32 v[92:93], v[80:81], v[80:81]
	v_pk_mul_f32 v[96:97], v[78:79], v[78:79]
	v_pk_add_f32 v[90:91], v[90:91], v[90:91] op_sel:[0,1] op_sel_hi:[1,0]
	v_pk_mov_b32 v[98:99], v[96:97], v[92:93] op_sel:[1,0]
	v_mov_b32_e32 v97, v93
	v_pk_add_f32 v[92:93], v[98:99], v[96:97]
	v_mul_f32_e32 v96, v66, v66
	v_mul_f32_e32 v97, v67, v67
	v_pk_add_f32 v[92:93], v[92:93], v[92:93] op_sel:[0,1] op_sel_hi:[1,0]
	v_mov_b32_e32 v91, v96
	v_mov_b32_e32 v93, v97
	v_pk_add_f32 v[90:91], v[90:91], v[92:93]
	v_mul_f32_e32 v92, v71, v71
	v_mul_f32_e32 v96, v73, v73
	v_mul_f32_e32 v98, v68, v68
	v_mul_f32_e32 v99, v69, v69
	v_pk_fma_f32 v[92:93], v[70:71], v[70:71], v[92:93] op_sel_hi:[1,1,0]
	v_pk_fma_f32 v[96:97], v[72:73], v[72:73], v[96:97] op_sel_hi:[1,1,0]
	v_mov_b32_e32 v93, v98
	v_mov_b32_e32 v97, v99
	v_pk_add_f32 v[92:93], v[92:93], v[96:97]
	v_pk_mul_f32 v[88:89], v[88:89], v[102:103] op_sel_hi:[1,0]
	v_pk_add_f32 v[90:91], v[90:91], v[92:93]
	v_pk_mul_f32 v[88:89], v[122:123], v[88:89]
	v_add_f32_e32 v90, v90, v91
	v_mov_b32_e32 v91, v90
	v_mov_b32_e32 v252, v90
	s_nop 1
	v_permlane16_swap_b32_e32 v91, v252
	v_add_f32_e32 v92, v252, v91
	v_mov_b32_e32 v93, v92
	v_mov_b32_e32 v252, v92
	v_pk_mul_f32 v[90:91], v[118:119], v[76:77]
	v_pk_mul_f32 v[76:77], v[120:121], v[74:75]
	v_cvt_pk_bf16_f32 v74, v86, v87
	v_cvt_pk_bf16_f32 v75, v88, v89
	s_nop 1
	v_permlane32_swap_b32_e32 v93, v252
	v_add_f32_e32 v86, v252, v93
	v_fmamk_f32 v86, v86, 0x3c800000, v180
	v_rsq_f32_e32 v86, v86
	v_cvt_pk_bf16_f32 v76, v76, v77
	v_cvt_pk_bf16_f32 v77, v90, v91
	s_nop 0
	v_mov_b32_e32 v248, v74
	v_mov_b32_e32 v249, v75
	v_mov_b32_e32 v250, v76
	v_mov_b32_e32 v251, v77
	v_mov_b32_dpp v248, v244 row_shl:8 row_mask:0xf bank_mask:0x3
	v_mov_b32_dpp v249, v245 row_shl:8 row_mask:0xf bank_mask:0x3
	v_mov_b32_dpp v250, v246 row_shl:8 row_mask:0xf bank_mask:0x3
	v_mov_b32_dpp v251, v247 row_shl:8 row_mask:0xf bank_mask:0x3
	v_mov_b32_dpp v244, v74 row_shr:8 row_mask:0xf bank_mask:0xc
	v_mov_b32_dpp v245, v75 row_shr:8 row_mask:0xf bank_mask:0xc
	v_mov_b32_dpp v246, v76 row_shr:8 row_mask:0xf bank_mask:0xc
	v_mov_b32_dpp v247, v77 row_shr:8 row_mask:0xf bank_mask:0xc
	global_store_dwordx4 v[240:241], v[244:247], off
	global_store_dwordx4 v[242:243], v[248:251], off
	v_pk_mul_f32 v[78:79], v[78:79], v[86:87] op_sel_hi:[1,0]
	v_pk_mul_f32 v[80:81], v[80:81], v[86:87] op_sel_hi:[1,0]
	v_pk_mul_f32 v[74:75], v[82:83], v[86:87] op_sel_hi:[1,0]
	v_pk_mul_f32 v[76:77], v[84:85], v[86:87] op_sel_hi:[1,0]
	v_pk_mul_f32 v[74:75], v[156:157], v[74:75]
	v_pk_mul_f32 v[76:77], v[154:155], v[76:77]
	v_pk_mul_f32 v[78:79], v[128:129], v[78:79]
	v_cvt_pk_bf16_f32 v74, v74, v75
	v_cvt_pk_bf16_f32 v75, v76, v77
	v_pk_mul_f32 v[80:81], v[126:127], v[80:81]
	v_cvt_pk_bf16_f32 v76, v78, v79
	v_add_co_u32_e32 v78, vcc, s66, v152
	v_cvt_pk_bf16_f32 v77, v80, v81
	v_pk_mul_f32 v[70:71], v[70:71], v[86:87] op_sel_hi:[1,0]
	s_nop 0
	v_addc_co_u32_e32 v79, vcc, 0, v153, vcc
	v_mov_b32_e32 v244, v74
	v_mov_b32_e32 v245, v75
	v_mov_b32_e32 v246, v76
	v_mov_b32_e32 v247, v77
	v_lshl_add_u64 v[240:241], v[78:79], 0, v[236:237]
	v_lshl_add_u64 v[242:243], v[78:79], 0, v[238:239]
	v_pk_mul_f32 v[70:71], v[124:125], v[70:71]
	v_pk_mul_f32 v[66:67], v[66:67], v[86:87] op_sel_hi:[1,0]
	v_pk_mul_f32 v[74:75], v[64:65], v[64:65]
	v_pk_mul_f32 v[76:77], v[62:63], v[62:63]
	v_pk_mul_f32 v[68:69], v[68:69], v[86:87] op_sel_hi:[1,0]
	v_pk_mov_b32 v[80:81], v[76:77], v[74:75] op_sel:[1,0]
	v_mov_b32_e32 v77, v75
	v_pk_add_f32 v[74:75], v[80:81], v[76:77]
	v_pk_mul_f32 v[76:77], v[60:61], v[60:61]
	v_pk_mul_f32 v[80:81], v[58:59], v[58:59]
	v_pk_add_f32 v[74:75], v[74:75], v[74:75] op_sel:[0,1] op_sel_hi:[1,0]
	v_pk_mov_b32 v[82:83], v[80:81], v[76:77] op_sel:[1,0]
	v_mov_b32_e32 v81, v77
	v_pk_add_f32 v[76:77], v[82:83], v[80:81]
	v_mul_f32_e32 v80, v42, v42
	v_mul_f32_e32 v81, v43, v43
	v_pk_add_f32 v[76:77], v[76:77], v[76:77] op_sel:[0,1] op_sel_hi:[1,0]
	v_mov_b32_e32 v75, v80
	v_mov_b32_e32 v77, v81
	v_pk_add_f32 v[74:75], v[74:75], v[76:77]
	v_mul_f32_e32 v76, v55, v55
	v_mul_f32_e32 v80, v57, v57
	v_mul_f32_e32 v82, v44, v44
	v_mul_f32_e32 v83, v45, v45
	v_pk_fma_f32 v[76:77], v[54:55], v[54:55], v[76:77] op_sel_hi:[1,1,0]
	v_pk_fma_f32 v[80:81], v[56:57], v[56:57], v[80:81] op_sel_hi:[1,1,0]
	v_mov_b32_e32 v77, v82
	v_mov_b32_e32 v81, v83
	v_pk_add_f32 v[76:77], v[76:77], v[80:81]
	v_pk_mul_f32 v[72:73], v[72:73], v[86:87] op_sel_hi:[1,0]
	v_pk_add_f32 v[74:75], v[74:75], v[76:77]
	v_pk_mul_f32 v[72:73], v[122:123], v[72:73]
	v_add_f32_e32 v74, v74, v75
	v_mov_b32_e32 v75, v74
	v_mov_b32_e32 v252, v74
	s_nop 1
	v_permlane16_swap_b32_e32 v75, v252
	v_add_f32_e32 v76, v252, v75
	v_mov_b32_e32 v77, v76
	v_mov_b32_e32 v252, v76
	v_pk_mul_f32 v[74:75], v[118:119], v[68:69]
	v_pk_mul_f32 v[68:69], v[120:121], v[66:67]
	v_cvt_pk_bf16_f32 v66, v70, v71
	v_cvt_pk_bf16_f32 v67, v72, v73
	s_nop 1
	v_permlane32_swap_b32_e32 v77, v252
	v_add_f32_e32 v70, v252, v77
	v_fmamk_f32 v70, v70, 0x3c800000, v180
; __device__ __forceinline__ unsigned cvt_pk_bf16(float lo, float hi) { unsigned r; asm volatile("v_cvt_pk_bf16_f32 %0, %1, %2" : "=v"(r) : "v"(lo), "v"(hi)); return r; }
;     __device__ __forceinline__ void operator()(const f32x4 (&acc)[2][2][4][2], const Unit& u, int wr, int wc, int fr, int fq) const {
;     ...
;                 for (int m = 0; m < 4; ++m) {
;                     float ss = 0.f;
; #pragma unroll
;                     for (int bj = 0; bj < 2; ++bj)
; #pragma unroll
;                         for (int n = 0; n < 2; ++n) { const f32x4 x = acc[ai][bj][m][n]; ss += (x[0] * x[0] + x[1] * x[1]) + (x[2] * x[2] + x[3] * x[3]); }
;                     ss += __shfl_xor(ss, 16); ss += __shfl_xor(ss, 32);
;                     const float rstd = __builtin_amdgcn_rsqf(ss * (1.0f / 64.0f) + eps);
;                     bf16_t* rowp = dst + (row0 + ai * HALF + m * 16) * 512 + colb;
; #pragma unroll
;                     for (int bj = 0; bj < 2; ++bj) { const f32x4 v0 = acc[ai][bj][m][0] * rstd * gv[bj][0], v1 = acc[ai][bj][m][1] * rstd * gv[bj][1];
;                         u32x4 w; w.x = cvt_pk_bf16(v0[0], v0[1]); w.y = cvt_pk_bf16(v0[2], v0[3]); w.z = cvt_pk_bf16(v1[0], v1[1]); w.w = cvt_pk_bf16(v1[2], v1[3]);
;                         *(u32x4*)(rowp + 32 * bj) = w; }
	v_rsq_f32_e32 v70, v70
	v_cvt_pk_bf16_f32 v68, v68, v69
	v_cvt_pk_bf16_f32 v69, v74, v75
	s_nop 0
	v_mov_b32_e32 v248, v66
	v_mov_b32_e32 v249, v67
	v_mov_b32_e32 v250, v68
	v_mov_b32_e32 v251, v69
	v_mov_b32_dpp v248, v244 row_shl:8 row_mask:0xf bank_mask:0x3
	v_mov_b32_dpp v249, v245 row_shl:8 row_mask:0xf bank_mask:0x3
	v_mov_b32_dpp v250, v246 row_shl:8 row_mask:0xf bank_mask:0x3
	v_mov_b32_dpp v251, v247 row_shl:8 row_mask:0xf bank_mask:0x3
	v_mov_b32_dpp v244, v66 row_shr:8 row_mask:0xf bank_mask:0xc
	v_mov_b32_dpp v245, v67 row_shr:8 row_mask:0xf bank_mask:0xc
	v_mov_b32_dpp v246, v68 row_shr:8 row_mask:0xf bank_mask:0xc
	v_mov_b32_dpp v247, v69 row_shr:8 row_mask:0xf bank_mask:0xc
	global_store_dwordx4 v[240:241], v[244:247], off
	global_store_dwordx4 v[242:243], v[248:251], off
	v_pk_mul_f32 v[62:63], v[62:63], v[70:71] op_sel_hi:[1,0]
	v_pk_mul_f32 v[58:59], v[58:59], v[70:71] op_sel_hi:[1,0]
	v_pk_mul_f32 v[62:63], v[156:157], v[62:63]
	v_pk_mul_f32 v[60:61], v[60:61], v[70:71] op_sel_hi:[1,0]
	v_pk_mul_f32 v[64:65], v[64:65], v[70:71] op_sel_hi:[1,0]
	v_pk_mul_f32 v[66:67], v[126:127], v[60:61]
	v_pk_mul_f32 v[60:61], v[128:129], v[58:59]
	v_cvt_pk_bf16_f32 v58, v62, v63
	v_add_co_u32_e32 v62, vcc, s69, v152
	v_pk_mul_f32 v[64:65], v[154:155], v[64:65]
	s_nop 0
	v_addc_co_u32_e32 v63, vcc, 0, v153, vcc
	v_cvt_pk_bf16_f32 v59, v64, v65
	v_cvt_pk_bf16_f32 v60, v60, v61
	v_cvt_pk_bf16_f32 v61, v66, v67
	v_mov_b32_e32 v244, v58
	v_mov_b32_e32 v245, v59
	v_mov_b32_e32 v246, v60
	v_mov_b32_e32 v247, v61
	v_lshl_add_u64 v[240:241], v[62:63], 0, v[236:237]
	v_lshl_add_u64 v[242:243], v[62:63], 0, v[238:239]
	v_pk_mul_f32 v[54:55], v[54:55], v[70:71] op_sel_hi:[1,0]
	v_pk_mul_f32 v[42:43], v[42:43], v[70:71] op_sel_hi:[1,0]
	v_pk_mul_f32 v[58:59], v[52:53], v[52:53]
	v_pk_mul_f32 v[60:61], v[50:51], v[50:51]
	v_pk_mul_f32 v[54:55], v[124:125], v[54:55]
	v_pk_mov_b32 v[64:65], v[60:61], v[58:59] op_sel:[1,0]
	v_mov_b32_e32 v61, v59
	v_pk_add_f32 v[58:59], v[64:65], v[60:61]
	v_pk_mul_f32 v[60:61], v[48:49], v[48:49]
	v_pk_mul_f32 v[64:65], v[46:47], v[46:47]
	v_pk_add_f32 v[58:59], v[58:59], v[58:59] op_sel:[0,1] op_sel_hi:[1,0]
	v_pk_mov_b32 v[66:67], v[64:65], v[60:61] op_sel:[1,0]
	v_mov_b32_e32 v65, v61
	v_pk_add_f32 v[60:61], v[66:67], v[64:65]
	v_mul_f32_e32 v64, v26, v26
	v_mul_f32_e32 v65, v27, v27
	v_pk_add_f32 v[60:61], v[60:61], v[60:61] op_sel:[0,1] op_sel_hi:[1,0]
	v_mov_b32_e32 v59, v64
	v_mov_b32_e32 v61, v65
	v_pk_add_f32 v[58:59], v[58:59], v[60:61]
	v_mul_f32_e32 v60, v39, v39
	v_mul_f32_e32 v64, v41, v41
	v_mul_f32_e32 v66, v28, v28
	v_mul_f32_e32 v67, v29, v29
	v_pk_fma_f32 v[60:61], v[38:39], v[38:39], v[60:61] op_sel_hi:[1,1,0]
	v_pk_fma_f32 v[64:65], v[40:41], v[40:41], v[64:65] op_sel_hi:[1,1,0]
	v_mov_b32_e32 v61, v66
	v_mov_b32_e32 v65, v67
	v_pk_add_f32 v[60:61], v[60:61], v[64:65]
	v_pk_mul_f32 v[44:45], v[44:45], v[70:71] op_sel_hi:[1,0]
	v_pk_add_f32 v[58:59], v[58:59], v[60:61]
	v_pk_mul_f32 v[56:57], v[56:57], v[70:71] op_sel_hi:[1,0]
	v_add_f32_e32 v58, v58, v59
	v_mov_b32_e32 v59, v58
	v_mov_b32_e32 v252, v58
	v_pk_mul_f32 v[56:57], v[122:123], v[56:57]
	s_nop 1
	v_permlane16_swap_b32_e32 v59, v252
	v_add_f32_e32 v60, v252, v59
	v_mov_b32_e32 v61, v60
	v_mov_b32_e32 v252, v60
	v_pk_mul_f32 v[58:59], v[118:119], v[44:45]
	v_pk_mul_f32 v[44:45], v[120:121], v[42:43]
	v_cvt_pk_bf16_f32 v42, v54, v55
	v_cvt_pk_bf16_f32 v43, v56, v57
	s_nop 1
	v_permlane32_swap_b32_e32 v61, v252
	v_add_f32_e32 v54, v252, v61
	v_fmamk_f32 v54, v54, 0x3c800000, v180
	v_rsq_f32_e32 v54, v54
	v_cvt_pk_bf16_f32 v44, v44, v45
	v_cvt_pk_bf16_f32 v45, v58, v59
	s_nop 0
	v_mov_b32_e32 v248, v42
	v_mov_b32_e32 v249, v43
	v_mov_b32_e32 v250, v44
	v_mov_b32_e32 v251, v45
	v_mov_b32_dpp v248, v244 row_shl:8 row_mask:0xf bank_mask:0x3
	v_mov_b32_dpp v249, v245 row_shl:8 row_mask:0xf bank_mask:0x3
	v_mov_b32_dpp v250, v246 row_shl:8 row_mask:0xf bank_mask:0x3
	v_mov_b32_dpp v251, v247 row_shl:8 row_mask:0xf bank_mask:0x3
	v_mov_b32_dpp v244, v42 row_shr:8 row_mask:0xf bank_mask:0xc
	v_mov_b32_dpp v245, v43 row_shr:8 row_mask:0xf bank_mask:0xc
	v_mov_b32_dpp v246, v44 row_shr:8 row_mask:0xf bank_mask:0xc
	v_mov_b32_dpp v247, v45 row_shr:8 row_mask:0xf bank_mask:0xc
	global_store_dwordx4 v[240:241], v[244:247], off
	global_store_dwordx4 v[242:243], v[248:251], off
	v_pk_mul_f32 v[46:47], v[46:47], v[54:55] op_sel_hi:[1,0]
	v_pk_mul_f32 v[48:49], v[48:49], v[54:55] op_sel_hi:[1,0]
	v_pk_mul_f32 v[42:43], v[50:51], v[54:55] op_sel_hi:[1,0]
	v_pk_mul_f32 v[44:45], v[52:53], v[54:55] op_sel_hi:[1,0]
	v_pk_mul_f32 v[42:43], v[156:157], v[42:43]
	v_pk_mul_f32 v[44:45], v[154:155], v[44:45]
	v_pk_mul_f32 v[46:47], v[128:129], v[46:47]
	v_cvt_pk_bf16_f32 v42, v42, v43
	v_cvt_pk_bf16_f32 v43, v44, v45
	v_pk_mul_f32 v[48:49], v[126:127], v[48:49]
	v_cvt_pk_bf16_f32 v44, v46, v47
	v_add_co_u32_e32 v46, vcc, s70, v152
	v_cvt_pk_bf16_f32 v45, v48, v49
	v_pk_mul_f32 v[38:39], v[38:39], v[54:55] op_sel_hi:[1,0]
	s_nop 0
	v_addc_co_u32_e32 v47, vcc, 0, v153, vcc
	v_mov_b32_e32 v244, v42
	v_mov_b32_e32 v245, v43
	v_mov_b32_e32 v246, v44
	v_mov_b32_e32 v247, v45
	v_lshl_add_u64 v[240:241], v[46:47], 0, v[236:237]
	v_lshl_add_u64 v[242:243], v[46:47], 0, v[238:239]
	v_pk_mul_f32 v[38:39], v[124:125], v[38:39]
	v_pk_mul_f32 v[26:27], v[26:27], v[54:55] op_sel_hi:[1,0]
	v_pk_mul_f32 v[42:43], v[36:37], v[36:37]
	v_pk_mul_f32 v[44:45], v[34:35], v[34:35]
	v_pk_mul_f32 v[28:29], v[28:29], v[54:55] op_sel_hi:[1,0]
	v_pk_mov_b32 v[48:49], v[44:45], v[42:43] op_sel:[1,0]
	v_mov_b32_e32 v45, v43
	v_pk_add_f32 v[42:43], v[48:49], v[44:45]
	v_pk_mul_f32 v[44:45], v[32:33], v[32:33]
; __device__ __forceinline__ unsigned cvt_pk_bf16(float lo, float hi) { unsigned r; asm volatile("v_cvt_pk_bf16_f32 %0, %1, %2" : "=v"(r) : "v"(lo), "v"(hi)); return r; }
;     __device__ __forceinline__ void operator()(const f32x4 (&acc)[2][2][4][2], const Unit& u, int wr, int wc, int fr, int fq) const {
;     ...
;                 for (int m = 0; m < 4; ++m) {
;                     float ss = 0.f;
; #pragma unroll
;                     for (int bj = 0; bj < 2; ++bj)
; #pragma unroll
;                         for (int n = 0; n < 2; ++n) { const f32x4 x = acc[ai][bj][m][n]; ss += (x[0] * x[0] + x[1] * x[1]) + (x[2] * x[2] + x[3] * x[3]); }
;                     ss += __shfl_xor(ss, 16); ss += __shfl_xor(ss, 32);
;                     const float rstd = __builtin_amdgcn_rsqf(ss * (1.0f / 64.0f) + eps);
;                     bf16_t* rowp = dst + (row0 + ai * HALF + m * 16) * 512 + colb;
; #pragma unroll
;                     for (int bj = 0; bj < 2; ++bj) { const f32x4 v0 = acc[ai][bj][m][0] * rstd * gv[bj][0], v1 = acc[ai][bj][m][1] * rstd * gv[bj][1];
;                         u32x4 w; w.x = cvt_pk_bf16(v0[0], v0[1]); w.y = cvt_pk_bf16(v0[2], v0[3]); w.z = cvt_pk_bf16(v1[0], v1[1]); w.w = cvt_pk_bf16(v1[2], v1[3]);
;                         *(u32x4*)(rowp + 32 * bj) = w; }
	v_pk_mul_f32 v[48:49], v[30:31], v[30:31]
	v_pk_add_f32 v[42:43], v[42:43], v[42:43] op_sel:[0,1] op_sel_hi:[1,0]
	v_pk_mov_b32 v[50:51], v[48:49], v[44:45] op_sel:[1,0]
	v_mov_b32_e32 v49, v45
	v_pk_add_f32 v[44:45], v[50:51], v[48:49]
	v_mul_f32_e32 v48, v10, v10
	v_mul_f32_e32 v49, v11, v11
	v_pk_add_f32 v[44:45], v[44:45], v[44:45] op_sel:[0,1] op_sel_hi:[1,0]
	v_mov_b32_e32 v43, v48
	v_mov_b32_e32 v45, v49
	v_pk_add_f32 v[42:43], v[42:43], v[44:45]
	v_mul_f32_e32 v44, v23, v23
	v_mul_f32_e32 v48, v25, v25
	v_mul_f32_e32 v50, v12, v12
	v_mul_f32_e32 v51, v13, v13
	v_pk_fma_f32 v[44:45], v[22:23], v[22:23], v[44:45] op_sel_hi:[1,1,0]
	v_pk_fma_f32 v[48:49], v[24:25], v[24:25], v[48:49] op_sel_hi:[1,1,0]
	v_mov_b32_e32 v45, v50
	v_mov_b32_e32 v49, v51
	v_pk_add_f32 v[44:45], v[44:45], v[48:49]
	v_pk_mul_f32 v[40:41], v[40:41], v[54:55] op_sel_hi:[1,0]
	v_pk_add_f32 v[42:43], v[42:43], v[44:45]
	v_pk_mul_f32 v[40:41], v[122:123], v[40:41]
	v_add_f32_e32 v42, v42, v43
	v_mov_b32_e32 v43, v42
	v_mov_b32_e32 v252, v42
	s_nop 1
	v_permlane16_swap_b32_e32 v43, v252
	v_add_f32_e32 v44, v252, v43
	v_mov_b32_e32 v45, v44
	v_mov_b32_e32 v252, v44
	v_pk_mul_f32 v[42:43], v[118:119], v[28:29]
	v_pk_mul_f32 v[28:29], v[120:121], v[26:27]
	v_cvt_pk_bf16_f32 v26, v38, v39
	v_cvt_pk_bf16_f32 v27, v40, v41
	s_nop 1
	v_permlane32_swap_b32_e32 v45, v252
	v_add_f32_e32 v38, v252, v45
	v_fmamk_f32 v38, v38, 0x3c800000, v180
	v_rsq_f32_e32 v38, v38
	v_cvt_pk_bf16_f32 v28, v28, v29
	v_cvt_pk_bf16_f32 v29, v42, v43
	s_nop 0
	v_mov_b32_e32 v248, v26
	v_mov_b32_e32 v249, v27
	v_mov_b32_e32 v250, v28
	v_mov_b32_e32 v251, v29
	v_mov_b32_dpp v248, v244 row_shl:8 row_mask:0xf bank_mask:0x3
	v_mov_b32_dpp v249, v245 row_shl:8 row_mask:0xf bank_mask:0x3
	v_mov_b32_dpp v250, v246 row_shl:8 row_mask:0xf bank_mask:0x3
	v_mov_b32_dpp v251, v247 row_shl:8 row_mask:0xf bank_mask:0x3
	v_mov_b32_dpp v244, v26 row_shr:8 row_mask:0xf bank_mask:0xc
	v_mov_b32_dpp v245, v27 row_shr:8 row_mask:0xf bank_mask:0xc
	v_mov_b32_dpp v246, v28 row_shr:8 row_mask:0xf bank_mask:0xc
	v_mov_b32_dpp v247, v29 row_shr:8 row_mask:0xf bank_mask:0xc
	global_store_dwordx4 v[240:241], v[244:247], off
	global_store_dwordx4 v[242:243], v[248:251], off
	v_pk_mul_f32 v[30:31], v[30:31], v[38:39] op_sel_hi:[1,0]
	v_pk_mul_f32 v[32:33], v[32:33], v[38:39] op_sel_hi:[1,0]
	v_pk_mul_f32 v[26:27], v[34:35], v[38:39] op_sel_hi:[1,0]
	v_pk_mul_f32 v[28:29], v[36:37], v[38:39] op_sel_hi:[1,0]
	v_pk_mul_f32 v[26:27], v[156:157], v[26:27]
	v_pk_mul_f32 v[28:29], v[154:155], v[28:29]
	v_pk_mul_f32 v[30:31], v[128:129], v[30:31]
	v_cvt_pk_bf16_f32 v26, v26, v27
	v_cvt_pk_bf16_f32 v27, v28, v29
	v_pk_mul_f32 v[32:33], v[126:127], v[32:33]
	v_cvt_pk_bf16_f32 v28, v30, v31
	v_add_co_u32_e32 v30, vcc, s71, v152
	v_cvt_pk_bf16_f32 v29, v32, v33
	v_pk_mul_f32 v[22:23], v[22:23], v[38:39] op_sel_hi:[1,0]
	s_nop 0
	v_addc_co_u32_e32 v31, vcc, 0, v153, vcc
	v_mov_b32_e32 v244, v26
	v_mov_b32_e32 v245, v27
	v_mov_b32_e32 v246, v28
	v_mov_b32_e32 v247, v29
	v_lshl_add_u64 v[240:241], v[30:31], 0, v[236:237]
	v_lshl_add_u64 v[242:243], v[30:31], 0, v[238:239]
	v_pk_mul_f32 v[22:23], v[124:125], v[22:23]
	v_pk_mul_f32 v[10:11], v[10:11], v[38:39] op_sel_hi:[1,0]
	v_pk_mul_f32 v[26:27], v[20:21], v[20:21]
	v_pk_mul_f32 v[28:29], v[18:19], v[18:19]
	v_pk_mul_f32 v[12:13], v[12:13], v[38:39] op_sel_hi:[1,0]
	v_pk_mov_b32 v[32:33], v[28:29], v[26:27] op_sel:[1,0]
	v_mov_b32_e32 v29, v27
	v_pk_add_f32 v[26:27], v[32:33], v[28:29]
	v_pk_mul_f32 v[28:29], v[16:17], v[16:17]
	v_pk_mul_f32 v[32:33], v[14:15], v[14:15]
	v_pk_add_f32 v[26:27], v[26:27], v[26:27] op_sel:[0,1] op_sel_hi:[1,0]
	v_pk_mov_b32 v[34:35], v[32:33], v[28:29] op_sel:[1,0]
	v_mov_b32_e32 v33, v29
	v_pk_add_f32 v[28:29], v[34:35], v[32:33]
	v_mul_f32_e32 v32, v2, v2
	v_mul_f32_e32 v33, v3, v3
	v_pk_add_f32 v[28:29], v[28:29], v[28:29] op_sel:[0,1] op_sel_hi:[1,0]
	v_mov_b32_e32 v27, v32
	v_mov_b32_e32 v29, v33
; __device__ __forceinline__ unsigned cvt_pk_bf16(float lo, float hi) { unsigned r; asm volatile("v_cvt_pk_bf16_f32 %0, %1, %2" : "=v"(r) : "v"(lo), "v"(hi)); return r; }
;     __device__ __forceinline__ void operator()(const f32x4 (&acc)[2][2][4][2], const Unit& u, int wr, int wc, int fr, int fq) const {
;     ...
;                 for (int m = 0; m < 4; ++m) {
;                     float ss = 0.f;
; #pragma unroll
;                     for (int bj = 0; bj < 2; ++bj)
; #pragma unroll
;                         for (int n = 0; n < 2; ++n) { const f32x4 x = acc[ai][bj][m][n]; ss += (x[0] * x[0] + x[1] * x[1]) + (x[2] * x[2] + x[3] * x[3]); }
;                     ss += __shfl_xor(ss, 16); ss += __shfl_xor(ss, 32);
;                     const float rstd = __builtin_amdgcn_rsqf(ss * (1.0f / 64.0f) + eps);
;                     bf16_t* rowp = dst + (row0 + ai * HALF + m * 16) * 512 + colb;
; #pragma unroll
;                     for (int bj = 0; bj < 2; ++bj) { const f32x4 v0 = acc[ai][bj][m][0] * rstd * gv[bj][0], v1 = acc[ai][bj][m][1] * rstd * gv[bj][1];
;                         u32x4 w; w.x = cvt_pk_bf16(v0[0], v0[1]); w.y = cvt_pk_bf16(v0[2], v0[3]); w.z = cvt_pk_bf16(v1[0], v1[1]); w.w = cvt_pk_bf16(v1[2], v1[3]);
;                         *(u32x4*)(rowp + 32 * bj) = w; }
	v_pk_add_f32 v[26:27], v[26:27], v[28:29]
	v_mul_f32_e32 v28, v7, v7
	v_mul_f32_e32 v32, v9, v9
	v_mul_f32_e32 v34, v4, v4
	v_mul_f32_e32 v35, v5, v5
	v_pk_fma_f32 v[28:29], v[6:7], v[6:7], v[28:29] op_sel_hi:[1,1,0]
	v_pk_fma_f32 v[32:33], v[8:9], v[8:9], v[32:33] op_sel_hi:[1,1,0]
	v_mov_b32_e32 v29, v34
	v_mov_b32_e32 v33, v35
	v_pk_add_f32 v[28:29], v[28:29], v[32:33]
	v_pk_mul_f32 v[24:25], v[24:25], v[38:39] op_sel_hi:[1,0]
	v_pk_add_f32 v[26:27], v[26:27], v[28:29]
	v_pk_mul_f32 v[24:25], v[122:123], v[24:25]
	v_add_f32_e32 v26, v26, v27
	v_mov_b32_e32 v27, v26
	v_mov_b32_e32 v252, v26
	s_nop 1
	v_permlane16_swap_b32_e32 v27, v252
	v_add_f32_e32 v28, v252, v27
	v_mov_b32_e32 v29, v28
	v_mov_b32_e32 v252, v28
	v_pk_mul_f32 v[26:27], v[118:119], v[12:13]
	v_pk_mul_f32 v[12:13], v[120:121], v[10:11]
	v_cvt_pk_bf16_f32 v10, v22, v23
	v_cvt_pk_bf16_f32 v11, v24, v25
	s_nop 1
	v_permlane32_swap_b32_e32 v29, v252
	v_add_f32_e32 v22, v252, v29
	v_fmamk_f32 v22, v22, 0x3c800000, v180
	v_rsq_f32_e32 v22, v22
	v_cvt_pk_bf16_f32 v12, v12, v13
	v_cvt_pk_bf16_f32 v13, v26, v27
	s_nop 0
	v_mov_b32_e32 v248, v10
	v_mov_b32_e32 v249, v11
	v_mov_b32_e32 v250, v12
	v_mov_b32_e32 v251, v13
	v_mov_b32_dpp v248, v244 row_shl:8 row_mask:0xf bank_mask:0x3
	v_mov_b32_dpp v249, v245 row_shl:8 row_mask:0xf bank_mask:0x3
	v_mov_b32_dpp v250, v246 row_shl:8 row_mask:0xf bank_mask:0x3
	v_mov_b32_dpp v251, v247 row_shl:8 row_mask:0xf bank_mask:0x3
	v_mov_b32_dpp v244, v10 row_shr:8 row_mask:0xf bank_mask:0xc
	v_mov_b32_dpp v245, v11 row_shr:8 row_mask:0xf bank_mask:0xc
	v_mov_b32_dpp v246, v12 row_shr:8 row_mask:0xf bank_mask:0xc
	v_mov_b32_dpp v247, v13 row_shr:8 row_mask:0xf bank_mask:0xc
	global_store_dwordx4 v[240:241], v[244:247], off
	global_store_dwordx4 v[242:243], v[248:251], off
	v_pk_mul_f32 v[14:15], v[14:15], v[22:23] op_sel_hi:[1,0]
	v_pk_mul_f32 v[16:17], v[16:17], v[22:23] op_sel_hi:[1,0]
	v_pk_mul_f32 v[10:11], v[18:19], v[22:23] op_sel_hi:[1,0]
	v_pk_mul_f32 v[12:13], v[20:21], v[22:23] op_sel_hi:[1,0]
	v_pk_mul_f32 v[10:11], v[156:157], v[10:11]
	v_pk_mul_f32 v[12:13], v[154:155], v[12:13]
	v_pk_mul_f32 v[14:15], v[128:129], v[14:15]
	v_cvt_pk_bf16_f32 v10, v10, v11
	v_cvt_pk_bf16_f32 v11, v12, v13
	v_pk_mul_f32 v[2:3], v[2:3], v[22:23] op_sel_hi:[1,0]
	v_cvt_pk_bf16_f32 v12, v14, v15
	v_add_co_u32_e32 v14, vcc, s72, v152
	v_pk_mul_f32 v[4:5], v[4:5], v[22:23] op_sel_hi:[1,0]
	s_nop 0
	v_addc_co_u32_e32 v15, vcc, 0, v153, vcc
	v_pk_mul_f32 v[16:17], v[126:127], v[16:17]
	v_pk_mul_f32 v[6:7], v[6:7], v[22:23] op_sel_hi:[1,0]
	v_cvt_pk_bf16_f32 v13, v16, v17
	v_mov_b32_e32 v244, v10
	v_mov_b32_e32 v245, v11
	v_mov_b32_e32 v246, v12
	v_mov_b32_e32 v247, v13
	v_lshl_add_u64 v[240:241], v[14:15], 0, v[236:237]
	v_lshl_add_u64 v[242:243], v[14:15], 0, v[238:239]
	v_pk_mul_f32 v[8:9], v[8:9], v[22:23] op_sel_hi:[1,0]
	v_pk_mul_f32 v[6:7], v[124:125], v[6:7]
	v_pk_mul_f32 v[10:11], v[118:119], v[4:5]
	v_pk_mul_f32 v[4:5], v[120:121], v[2:3]
	v_pk_mul_f32 v[8:9], v[122:123], v[8:9]
	v_cvt_pk_bf16_f32 v2, v6, v7
	s_nop 0
	v_cvt_pk_bf16_f32 v3, v8, v9
	v_cvt_pk_bf16_f32 v4, v4, v5
	v_cvt_pk_bf16_f32 v5, v10, v11
	s_nop 0
	v_mov_b32_e32 v248, v2
	v_mov_b32_e32 v249, v3
	v_mov_b32_e32 v250, v4
	v_mov_b32_e32 v251, v5
	v_mov_b32_dpp v248, v244 row_shl:8 row_mask:0xf bank_mask:0x3
	v_mov_b32_dpp v249, v245 row_shl:8 row_mask:0xf bank_mask:0x3
	v_mov_b32_dpp v250, v246 row_shl:8 row_mask:0xf bank_mask:0x3
	v_mov_b32_dpp v251, v247 row_shl:8 row_mask:0xf bank_mask:0x3
	v_mov_b32_dpp v244, v2 row_shr:8 row_mask:0xf bank_mask:0xc
	v_mov_b32_dpp v245, v3 row_shr:8 row_mask:0xf bank_mask:0xc
	v_mov_b32_dpp v246, v4 row_shr:8 row_mask:0xf bank_mask:0xc
	v_mov_b32_dpp v247, v5 row_shr:8 row_mask:0xf bank_mask:0xc
	global_store_dwordx4 v[240:241], v[244:247], off
	global_store_dwordx4 v[242:243], v[248:251], off
	s_andn2_b64 vcc, exec, s[4:5]
	s_mov_b64 s[4:5], -1
	s_cbranch_vccnz .LBB0_230
